# grid barrier: non-leader workgroups issue their L1 invalidate before polling the release word instead of after
# speedup vs baseline: 1.0050x; 1.0050x over previous
.LBB0_135:
	s_or_b64 exec, exec, s[14:15]
	v_cvt_f32_u32_e32 v4, v2
	s_waitcnt vmcnt(0)
	v_readfirstlane_b32 s3, v3
	v_sub_u32_e32 v3, 0, v2
	v_rcp_iflag_f32_e32 v4, v4
	v_add_u32_e32 v5, s3, v1
	v_mul_f32_e32 v4, 0x4f7ffffe, v4
	v_cvt_u32_f32_e32 v4, v4
	v_mul_lo_u32 v1, v3, v4
	v_mul_hi_u32 v1, v4, v1
	v_add_u32_e32 v1, v4, v1
	v_mul_hi_u32 v1, v5, v1
	v_mul_lo_u32 v3, v1, v2
	v_sub_u32_e32 v3, v5, v3
	v_add_u32_e32 v4, 1, v1
	v_cmp_ge_u32_e32 vcc, v3, v2
	s_nop 1
	v_cndmask_b32_e32 v1, v1, v4, vcc
	v_sub_u32_e32 v4, v3, v2
	v_cndmask_b32_e32 v3, v3, v4, vcc
	v_add_u32_e32 v4, 1, v1
	v_cmp_ge_u32_e32 vcc, v3, v2
	v_add_u32_e32 v3, 1, v5
	s_nop 0
	v_cndmask_b32_e32 v1, v1, v4, vcc
	v_mul_lo_u32 v4, v2, v1
	v_add_u32_e32 v2, v4, v2
	v_cmp_ne_u32_e32 vcc, v3, v2
	s_and_saveexec_b64 s[12:13], vcc
	s_xor_b64 s[12:13], exec, s[12:13]
	s_cbranch_execz .LBB0_149
	s_waitcnt lgkmcnt(0)
	buffer_inv sc1
	v_mov_b32_e32 v0, 0x2000
	global_load_dword v0, v0, s[10:11] offset:1024 sc1
	s_add_u32 s18, s10, 0x2400
	s_addc_u32 s19, s11, 0
	s_waitcnt vmcnt(0)
	v_cmp_eq_u32_e32 vcc, v0, v1
	s_and_saveexec_b64 s[14:15], vcc
	s_cbranch_execz .LBB0_148
	s_add_u32 s16, s58, 0x4200
	s_addc_u32 s17, s59, 0
	s_mov_b32 s3, 1
	s_mov_b64 s[20:21], 0
	v_mov_b32_e32 v0, 0
	s_branch .LBB0_139

.LBB0_148:
	s_or_b64 exec, exec, s[14:15]
	s_waitcnt vmcnt(0)
	s_waitcnt vmcnt(0)

.LBB0_2990:
	s_or_b64 exec, exec, s[12:13]
	v_cvt_f32_u32_e32 v4, v2
	s_waitcnt vmcnt(0)
	v_readfirstlane_b32 s3, v3
	v_sub_u32_e32 v3, 0, v2
	v_rcp_iflag_f32_e32 v4, v4
	v_add_u32_e32 v5, s3, v1
	v_mul_f32_e32 v4, 0x4f7ffffe, v4
	v_cvt_u32_f32_e32 v4, v4
	v_mul_lo_u32 v1, v3, v4
	v_mul_hi_u32 v1, v4, v1
	v_add_u32_e32 v1, v4, v1
	v_mul_hi_u32 v1, v5, v1
	v_mul_lo_u32 v3, v1, v2
	v_sub_u32_e32 v3, v5, v3
	v_add_u32_e32 v4, 1, v1
	v_cmp_ge_u32_e32 vcc, v3, v2
	s_nop 1
	v_cndmask_b32_e32 v1, v1, v4, vcc
	v_sub_u32_e32 v4, v3, v2
	v_cndmask_b32_e32 v3, v3, v4, vcc
	v_add_u32_e32 v4, 1, v1
	v_cmp_ge_u32_e32 vcc, v3, v2
	v_add_u32_e32 v3, 1, v5
	s_nop 0
	v_cndmask_b32_e32 v1, v1, v4, vcc
	v_mul_lo_u32 v4, v2, v1
	v_add_u32_e32 v2, v4, v2
	v_cmp_ne_u32_e32 vcc, v3, v2
	s_and_saveexec_b64 s[10:11], vcc
	s_xor_b64 s[10:11], exec, s[10:11]
	s_cbranch_execz .LBB0_3004
	s_waitcnt lgkmcnt(0)
	buffer_inv sc1
	v_mov_b32_e32 v0, 0x2000
	global_load_dword v0, v0, s[4:5] offset:1024 sc1
	s_add_u32 s16, s4, 0x2400
	s_addc_u32 s17, s5, 0
	s_waitcnt vmcnt(0)
	v_cmp_eq_u32_e32 vcc, v0, v1
	s_and_saveexec_b64 s[12:13], vcc
	s_cbranch_execz .LBB0_3003
	s_add_u32 s14, s58, 0x4200
	s_addc_u32 s15, s59, 0
	s_mov_b32 s3, 1
	s_mov_b64 s[18:19], 0
	v_mov_b32_e32 v0, 0
	s_branch .LBB0_2994

.LBB0_3003:
	s_or_b64 exec, exec, s[12:13]
	s_waitcnt vmcnt(0)
	s_waitcnt vmcnt(0)
